# v106 + attention zero-reference path: guard branches inverted to fall through on the common path, causal-mask blocks moved out of line
# speedup vs baseline: 1.0157x; 1.0067x over previous
; template <bool HAS_PV, bool HAS_QK, bool C1> ...
;     s16x4 vlo[2], vhi[2]; bf16x8 ka, qa;
;     if (HAS_PV) {
; #pragma unroll
;         for (int u = 0; u < 2; ++u) { vlo[u] = vtr(vb + vaddr[0] + u * 512); vhi[u] = vtr(vb + vaddr[1] + u * 512); } }
;     if (HAS_QK) { const int ad = C1 ? sub1(kaddr[0]) : kaddr[0]; ka = *(const ATT_LAS bf16x8*)(kb + ad); qa = *(const ATT_LAS bf16x8*)(qb_ + ad);
; #pragma unroll
;         for (int i = 0; i < 16; ++i) Snext[i] = 0.f; }
;     float sa = 0.f, sb = 0.f;
; #pragma unroll
;     for (int g = 0; g < 4; ++g) {
;         s16x4 nlo[2], nhi[2]; bf16x8 nk, nq;
;         if (g < 3) {
;             if (HAS_PV) {
; #pragma unroll
;                 for (int u = 0; u < 2; ++u) { const int off = (2 * ((g + 1) & 1) + u) * 512 + ((g + 1) >> 1) * 4096; nlo[u] = vtr(vb + vaddr[0] + off); nhi[u] = vtr(vb + vaddr[1] + off); } }
;             if (HAS_QK) { const int ad = C1 ? sub1(kaddr[g + 1]) : kaddr[g + 1]; nk = *(const ATT_LAS bf16x8*)(kb + ad); nq = *(const ATT_LAS bf16x8*)(qb_ + ad); }
;         }
;         if (HAS_PV) { const bf16x8 pa = __builtin_bit_cast(bf16x8, pkin[g >> 1]);
; #pragma unroll
;             for (int u = 0; u < 2; ++u) { const bf16x8 vf = __builtin_shufflevector(vlo[u], vhi[u], 0, 1, 2, 3, 4, 5, 6, 7); Opv[2 * (g & 1) + u] = ATT_MFMA(pa, vf, Opv[2 * (g & 1) + u]); } }
;         if (HAS_QK) Snext = ATT_MFMA(ka, qa, Snext);
; #pragma unroll
;         for (int e = 4 * g; e < 4 * g + 4; e += 2) { Scur[e] = __builtin_amdgcn_exp2f(Scur[e] - m); Scur[e + 1] = __builtin_amdgcn_exp2f(Scur[e + 1] - m); sa += Scur[e]; sb += Scur[e + 1]; }
;         if (g & 1) pkout[g >> 1] = (u32x4){cvtpk(Scur[4 * g - 4], Scur[4 * g - 3]), cvtpk(Scur[4 * g - 2], Scur[4 * g - 1]), cvtpk(Scur[4 * g], Scur[4 * g + 1]), cvtpk(Scur[4 * g + 2], Scur[4 * g + 3])};
;         if (g < 3) {
;             if (HAS_PV) {
; #pragma unroll
;                 for (int u = 0; u < 2; ++u) { vlo[u] = nlo[u]; vhi[u] = nhi[u]; } }
;             if (HAS_QK) { ka = nk; qa = nq; }
;         }
;         __builtin_amdgcn_sched_barrier(0);
;     }
;     l += sa + sb;
;     return sa + sb;
; }
; __device__ __forceinline__ void tile_body(bool MASK, const ATT_LAS unsigned char* kb, const ATT_LAS unsigned char* vb, const ATT_LAS unsigned char* qbase, const int (&kaddr)[4], const int (&vaddr)[2], ...
;     ...
;     qk_issue<false>(Sa, kb, qbase, kaddr);
.Lns_296:
	ds_read_b128 v[2:5], v248
	ds_read_b128 v[6:9], v244
	s_nop 1
	ds_read_b128 v[10:13], v249
	ds_read_b128 v[146:149], v245
	v_exp_f32_e32 v15, v170
	v_exp_f32_e32 v14, v171
	v_exp_f32_e32 v155, v172
	v_exp_f32_e32 v154, v173
	s_waitcnt lgkmcnt(2)
	v_mfma_f32_32x32x16_bf16 v[158:173], v[2:5], v[6:9], 0
	s_waitcnt lgkmcnt(0)
	v_mfma_f32_32x32x16_bf16 v[158:173], v[10:13], v[146:149], v[158:173]
	ds_read_b128 v[6:9], v250
	ds_read_b128 v[150:153], v246
	v_exp_f32_e32 v157, v174
	v_exp_f32_e32 v156, v175
	v_exp_f32_e32 v175, v176
	v_exp_f32_e32 v174, v177
	v_cvt_pk_bf16_f32 v2, v15, v14
	v_cvt_pk_bf16_f32 v3, v155, v154
	v_cvt_pk_bf16_f32 v4, v157, v156
	v_cvt_pk_bf16_f32 v5, v175, v174
	s_waitcnt lgkmcnt(0)
	v_mfma_f32_32x32x16_bf16 v[158:173], v[6:9], v[150:153], v[158:173]
	ds_read_b128 v[10:13], v251
	ds_read_b128 v[146:149], v247
	v_exp_f32_e32 v177, v178
	v_exp_f32_e32 v176, v179
	v_exp_f32_e32 v179, v180
	v_exp_f32_e32 v178, v181
	s_waitcnt lgkmcnt(0)
	v_mfma_f32_32x32x16_bf16 v[158:173], v[10:13], v[146:149], v[158:173]
	v_exp_f32_e32 v7, v182
	v_add_f32_e32 v14, v154, v14
	v_add_f32_e32 v15, v155, v15
	v_exp_f32_e32 v6, v183
	v_exp_f32_e32 v9, v184
	v_add_f32_e32 v14, v156, v14
	v_add_f32_e32 v15, v157, v15
	v_exp_f32_e32 v8, v185
	v_add_f32_e32 v14, v174, v14
	v_add_f32_e32 v15, v175, v15
	v_cvt_pk_bf16_f32 v10, v177, v176
	v_cvt_pk_bf16_f32 v11, v179, v178
	v_cvt_pk_bf16_f32 v12, v7, v6
	v_cvt_pk_bf16_f32 v13, v9, v8
	v_add_f32_e32 v14, v176, v14
	v_add_f32_e32 v15, v177, v15
	v_add_f32_e32 v14, v178, v14
	v_add_f32_e32 v15, v179, v15
	v_add_f32_e32 v6, v6, v14
	v_add_f32_e32 v7, v7, v15
	v_add_f32_e32 v6, v8, v6
	v_add_f32_e32 v7, v9, v7
	v_add_f32_e32 v6, v6, v7
	v_cmp_nge_f32_e32 vcc, s58, v6
	s_andn2_b64 s[4:5], exec, s[36:37]
	s_cbranch_vccnz .Lslow_1
.Lns_305:
	v_add_f32_e32 v180, v225, v6
	s_and_b64 vcc, exec, s[4:5]
	s_cbranch_vccz .Lns_308
.Lns_311:
	s_and_b32 vcc_lo, s79, 1
	s_lshl_b32 vcc_lo, vcc_lo, 14
	s_add_i32 m0, vcc_lo, s50
	s_cmp_ge_u32 s79, s76
	s_cbranch_scc1 .Ldma_ns2
	global_load_lds_dwordx4 v200, s[92:93]
.Ldma_ns2:
	v_add_u32_e32 v178, s81, v213
	v_add_u32_e32 v179, s81, v207
	ds_read_b64_tr_b16 v[8:9], v178 offset:34816
	ds_read_b64_tr_b16 v[6:7], v179 offset:32768
	ds_read_b64_tr_b16 v[146:147], v179 offset:33280
	ds_read_b64_tr_b16 v[174:175], v179 offset:33792
	ds_read_b64_tr_b16 v[182:183], v179 offset:34304
	ds_read_b64_tr_b16 v[148:149], v178 offset:35328
	ds_read_b64_tr_b16 v[176:177], v178 offset:35840
	ds_read_b64_tr_b16 v[184:185], v178 offset:36352
	s_waitcnt lgkmcnt(6)
	v_mfma_f32_32x32x16_bf16 v[34:49], v[2:5], v[6:9], v[34:49]
	ds_read_b128 v[6:9], v216 offset:8192
	ds_read_b128 v[150:153], v217
	ds_read_b128 v[186:189], v218 offset:8192
	ds_read_b128 v[226:229], v219
	v_exp_f32_e32 v15, v158
	v_exp_f32_e32 v239, v160
	s_waitcnt lgkmcnt(6)
	v_mfma_f32_32x32x16_bf16 v[50:65], v[2:5], v[146:149], v[50:65]
	v_exp_f32_e32 v14, v159
	v_exp_f32_e32 v238, v161
	s_waitcnt lgkmcnt(2)
	v_mfma_f32_32x32x16_bf16 v[146:161], v[6:9], v[150:153], 0
	v_mfma_f32_32x32x16_bf16 v[66:81], v[2:5], v[174:177], v[66:81]
	ds_read_b64_tr_b16 v[6:7], v179 offset:36864
	ds_read_b64_tr_b16 v[8:9], v178 offset:38912
	ds_read_b64_tr_b16 v[176:177], v178 offset:39424
	ds_read_b64_tr_b16 v[174:175], v179 offset:37376
	ds_read_b128 v[230:233], v220 offset:8192
	ds_read_b128 v[234:237], v221
	v_exp_f32_e32 v241, v162
	v_exp_f32_e32 v240, v163
	v_mfma_f32_32x32x16_bf16 v[82:97], v[2:5], v[182:185], v[82:97]
	v_exp_f32_e32 v243, v164
	v_exp_f32_e32 v242, v165
	v_cvt_pk_bf16_f32 v2, v15, v14
	v_cvt_pk_bf16_f32 v3, v239, v238
	v_cvt_pk_bf16_f32 v4, v241, v240
	s_waitcnt lgkmcnt(6)
	v_mfma_f32_32x32x16_bf16 v[146:161], v[186:189], v[226:229], v[146:161]
	v_cvt_pk_bf16_f32 v5, v243, v242
	s_waitcnt lgkmcnt(4)
	v_mfma_f32_32x32x16_bf16 v[34:49], v[10:13], v[6:9], v[34:49]
	ds_read_b64_tr_b16 v[6:7], v179 offset:37888
	ds_read_b64_tr_b16 v[8:9], v178 offset:39936
	ds_read_b64_tr_b16 v[164:165], v178 offset:40448
	ds_read_b64_tr_b16 v[162:163], v179 offset:38400
	ds_read_b128 v[182:185], v222 offset:8192
	ds_read_b128 v[186:189], v223
	s_waitcnt lgkmcnt(8)
	v_mfma_f32_32x32x16_bf16 v[50:65], v[10:13], v[174:177], v[50:65]
	v_exp_f32_e32 v175, v166
	v_exp_f32_e32 v174, v167
	v_exp_f32_e32 v167, v168
	v_exp_f32_e32 v166, v169
	s_waitcnt lgkmcnt(6)
	v_mfma_f32_32x32x16_bf16 v[146:161], v[230:233], v[234:237], v[146:161]
	s_waitcnt lgkmcnt(4)
	v_mfma_f32_32x32x16_bf16 v[66:81], v[10:13], v[6:9], v[66:81]
	v_exp_f32_e32 v169, v170
	v_exp_f32_e32 v168, v171
	v_exp_f32_e32 v171, v172
	v_exp_f32_e32 v170, v173
	s_waitcnt lgkmcnt(2)
	v_mfma_f32_32x32x16_bf16 v[82:97], v[10:13], v[162:165], v[82:97]
	v_cvt_pk_bf16_f32 v6, v175, v174
	v_cvt_pk_bf16_f32 v7, v167, v166
	v_cvt_pk_bf16_f32 v8, v169, v168
	v_cvt_pk_bf16_f32 v9, v171, v170
	v_add_f32_e64 v10, v238, v14
	v_add_f32_e64 v11, v239, v15
	s_waitcnt lgkmcnt(0)
	v_mfma_f32_32x32x16_bf16 v[146:161], v[182:185], v[186:189], v[146:161]
	v_add_f32_e64 v10, v240, v10
	v_add_f32_e64 v11, v241, v11
	v_add_f32_e64 v10, v242, v10
	v_add_f32_e64 v11, v243, v11
	v_add_f32_e64 v10, v174, v10
	v_add_f32_e64 v11, v175, v11
	v_add_f32_e32 v10, v166, v10
	v_add_f32_e32 v11, v167, v11
	v_add_f32_e32 v10, v168, v10
	v_add_f32_e32 v11, v169, v11
	v_add_f32_e32 v10, v170, v10
	v_add_f32_e32 v11, v171, v11
	v_add_f32_e32 v10, v10, v11
	v_cmp_nge_f32_e32 vcc, s58, v10
	s_cbranch_vccnz .Lslow_2
.Lns_320:
	v_add_f32_e32 v181, v224, v10
	s_and_b64 vcc, exec, s[4:5]
	s_cbranch_vccz .Lns_323
.Lns_326:
	s_and_b32 vcc_lo, s79, 1
	s_lshl_b32 vcc_lo, vcc_lo, 14
	s_add_i32 vcc_lo, vcc_lo, s50
	s_add_i32 m0, vcc_lo, 0x8000
	s_cmp_ge_u32 s79, s76
	s_cbranch_scc1 .Ldma_ns3
	global_load_lds_dwordx4 v201, s[94:95]
; template <bool HAS_PV, bool HAS_QK, bool C1> ...
;     s16x4 vlo[2], vhi[2]; bf16x8 ka, qa;
;     if (HAS_PV) {
; #pragma unroll
;         for (int u = 0; u < 2; ++u) { vlo[u] = vtr(vb + vaddr[0] + u * 512); vhi[u] = vtr(vb + vaddr[1] + u * 512); } }
;     if (HAS_QK) { const int ad = C1 ? sub1(kaddr[0]) : kaddr[0]; ka = *(const ATT_LAS bf16x8*)(kb + ad); qa = *(const ATT_LAS bf16x8*)(qb_ + ad);
; #pragma unroll
;         for (int i = 0; i < 16; ++i) Snext[i] = 0.f; }
;     float sa = 0.f, sb = 0.f;
; #pragma unroll
;     for (int g = 0; g < 4; ++g) {
;         s16x4 nlo[2], nhi[2]; bf16x8 nk, nq;
;         if (g < 3) {
;             if (HAS_PV) {
; #pragma unroll
;                 for (int u = 0; u < 2; ++u) { const int off = (2 * ((g + 1) & 1) + u) * 512 + ((g + 1) >> 1) * 4096; nlo[u] = vtr(vb + vaddr[0] + off); nhi[u] = vtr(vb + vaddr[1] + off); } }
;             if (HAS_QK) { const int ad = C1 ? sub1(kaddr[g + 1]) : kaddr[g + 1]; nk = *(const ATT_LAS bf16x8*)(kb + ad); nq = *(const ATT_LAS bf16x8*)(qb_ + ad); }
;         }
;         if (HAS_PV) { const bf16x8 pa = __builtin_bit_cast(bf16x8, pkin[g >> 1]);
; #pragma unroll
;             for (int u = 0; u < 2; ++u) { const bf16x8 vf = __builtin_shufflevector(vlo[u], vhi[u], 0, 1, 2, 3, 4, 5, 6, 7); Opv[2 * (g & 1) + u] = ATT_MFMA(pa, vf, Opv[2 * (g & 1) + u]); } }
;         if (HAS_QK) Snext = ATT_MFMA(ka, qa, Snext);
; #pragma unroll
;         for (int e = 4 * g; e < 4 * g + 4; e += 2) { Scur[e] = __builtin_amdgcn_exp2f(Scur[e] - m); Scur[e + 1] = __builtin_amdgcn_exp2f(Scur[e + 1] - m); sa += Scur[e]; sb += Scur[e + 1]; }
;         if (g & 1) pkout[g >> 1] = (u32x4){cvtpk(Scur[4 * g - 4], Scur[4 * g - 3]), cvtpk(Scur[4 * g - 2], Scur[4 * g - 1]), cvtpk(Scur[4 * g], Scur[4 * g + 1]), cvtpk(Scur[4 * g + 2], Scur[4 * g + 3])};
;         if (g < 3) {
;             if (HAS_PV) {
; #pragma unroll
;                 for (int u = 0; u < 2; ++u) { vlo[u] = nlo[u]; vhi[u] = nhi[u]; } }
;             if (HAS_QK) { ka = nk; qa = nq; }
;         }
;         __builtin_amdgcn_sched_barrier(0);
;     }
;     l += sa + sb;
;     return sa + sb;
; }
; __device__ __forceinline__ void tile_body(bool MASK, const ATT_LAS unsigned char* kb, const ATT_LAS unsigned char* vb, const ATT_LAS unsigned char* qbase, const int (&kaddr)[4], const int (&vaddr)[2], ...
;     ...
;     apply_mask(MASK, Sa, kvrel + 32, r, h); ls = l1;
.Ldma_ns3:
	ds_read_b64_tr_b16 v[10:11], v179 offset:32768
	ds_read_b64_tr_b16 v[12:13], v178 offset:34816
	ds_read_b64_tr_b16 v[164:165], v178 offset:35328
	ds_read_b64_tr_b16 v[162:163], v179 offset:33280
	s_waitcnt lgkmcnt(2)
	v_mfma_f32_32x32x16_bf16 v[130:145], v[2:5], v[10:13], v[130:145]
	ds_read_b128 v[166:169], v248 offset:8192
	ds_read_b128 v[170:173], v244
	ds_read_b64_tr_b16 v[10:11], v179 offset:33792
	ds_read_b64_tr_b16 v[12:13], v178 offset:35840
	ds_read_b64_tr_b16 v[184:185], v178 offset:36352
	ds_read_b64_tr_b16 v[182:183], v179 offset:34304
	s_waitcnt lgkmcnt(6)
	v_mfma_f32_32x32x16_bf16 v[114:129], v[2:5], v[162:165], v[114:129]
	ds_read_b128 v[186:189], v249 offset:8192
	ds_read_b128 v[224:227], v245
	v_exp_f32_e32 v15, v146
	v_exp_f32_e32 v237, v148
	s_waitcnt lgkmcnt(6)
	v_mfma_f32_32x32x16_bf16 v[162:177], v[166:169], v[170:173], 0
	v_exp_f32_e32 v14, v147
	v_exp_f32_e32 v236, v149
	s_waitcnt lgkmcnt(4)
	v_mfma_f32_32x32x16_bf16 v[98:113], v[2:5], v[10:13], v[98:113]
	ds_read_b64_tr_b16 v[146:147], v179 offset:36864
	ds_read_b64_tr_b16 v[148:149], v178 offset:38912
	ds_read_b64_tr_b16 v[230:231], v178 offset:39424
	ds_read_b64_tr_b16 v[228:229], v179 offset:37376
	ds_read_b128 v[10:13], v250 offset:8192
	ds_read_b128 v[232:235], v246
	s_waitcnt lgkmcnt(8)
	v_mfma_f32_32x32x16_bf16 v[18:33], v[2:5], v[182:185], v[18:33]
	v_exp_f32_e32 v239, v150
	v_exp_f32_e32 v241, v152
	v_exp_f32_e32 v238, v151
	s_waitcnt lgkmcnt(6)
	v_mfma_f32_32x32x16_bf16 v[162:177], v[186:189], v[224:227], v[162:177]
	v_exp_f32_e32 v240, v153
	v_cvt_pk_bf16_f32 v2, v15, v14
	v_cvt_pk_bf16_f32 v3, v237, v236
	v_cvt_pk_bf16_f32 v4, v239, v238
	v_cvt_pk_bf16_f32 v5, v241, v240
	s_waitcnt lgkmcnt(4)
	v_mfma_f32_32x32x16_bf16 v[130:145], v[6:9], v[146:149], v[130:145]
	ds_read_b64_tr_b16 v[146:147], v179 offset:37888
	ds_read_b64_tr_b16 v[148:149], v178 offset:39936
	ds_read_b64_tr_b16 v[152:153], v178 offset:40448
	ds_read_b64_tr_b16 v[150:151], v179 offset:38400
	ds_read_b128 v[182:185], v251 offset:8192
	ds_read_b128 v[186:189], v247
	s_waitcnt lgkmcnt(8)
	v_mfma_f32_32x32x16_bf16 v[114:129], v[6:9], v[228:231], v[114:129]
	v_exp_f32_e32 v225, v154
	v_exp_f32_e32 v224, v155
	v_exp_f32_e32 v155, v156
	s_waitcnt lgkmcnt(6)
	v_mfma_f32_32x32x16_bf16 v[162:177], v[10:13], v[232:235], v[162:177]
	v_exp_f32_e32 v154, v157
	v_exp_f32_e32 v157, v158
	s_waitcnt lgkmcnt(4)
	v_mfma_f32_32x32x16_bf16 v[98:113], v[6:9], v[146:149], v[98:113]
	v_exp_f32_e32 v156, v159
	v_exp_f32_e32 v147, v160
	v_exp_f32_e32 v146, v161
	v_cvt_pk_bf16_f32 v10, v225, v224
	v_cvt_pk_bf16_f32 v11, v155, v154
	s_waitcnt lgkmcnt(2)
	v_mfma_f32_32x32x16_bf16 v[18:33], v[6:9], v[150:153], v[18:33]
	v_cvt_pk_bf16_f32 v12, v157, v156
	v_cvt_pk_bf16_f32 v13, v147, v146
	v_add_f32_e64 v6, v236, v14
	v_add_f32_e64 v7, v237, v15
	v_add_f32_e64 v6, v238, v6
	v_add_f32_e64 v7, v239, v7
	s_waitcnt lgkmcnt(0)
	v_mfma_f32_32x32x16_bf16 v[162:177], v[182:185], v[186:189], v[162:177]
	v_add_f32_e64 v6, v240, v6
	v_add_f32_e64 v7, v241, v7
	v_add_f32_e64 v6, v224, v6
	v_add_f32_e64 v7, v225, v7
	v_add_f32_e64 v6, v154, v6
	v_add_f32_e64 v7, v155, v7
	v_add_f32_e32 v6, v156, v6
	v_add_f32_e32 v7, v157, v7
	v_add_f32_e32 v6, v146, v6
	v_add_f32_e32 v7, v147, v7
	v_add_f32_e32 v6, v6, v7
	v_cmp_nge_f32_e32 vcc, s58, v6
	s_cbranch_vccnz .Lslow_3
.Lns_335:
	v_add_f32_e32 v225, v180, v6
	s_and_b64 vcc, exec, s[4:5]
	s_cbranch_vccz .Lns_338
.Lns_341:
	ds_read_b64_tr_b16 v[8:9], v178 offset:43008
	ds_read_b64_tr_b16 v[6:7], v179 offset:40960
	ds_read_b64_tr_b16 v[146:147], v179 offset:41472
	ds_read_b64_tr_b16 v[150:151], v179 offset:41984
	ds_read_b64_tr_b16 v[154:155], v179 offset:42496
	ds_read_b64_tr_b16 v[148:149], v178 offset:43520
	ds_read_b64_tr_b16 v[152:153], v178 offset:44032
	ds_read_b64_tr_b16 v[156:157], v178 offset:44544
	s_waitcnt lgkmcnt(6)
	v_mfma_f32_32x32x16_bf16 v[34:49], v[2:5], v[6:9], v[34:49]
	v_exp_f32_e32 v15, v162
	v_exp_f32_e32 v14, v163
	v_exp_f32_e32 v163, v164
	s_waitcnt lgkmcnt(2)
	v_mfma_f32_32x32x16_bf16 v[50:65], v[2:5], v[146:149], v[50:65]
	v_exp_f32_e32 v162, v165
	s_waitcnt lgkmcnt(1)
	v_mfma_f32_32x32x16_bf16 v[66:81], v[2:5], v[150:153], v[66:81]
	ds_read_b64_tr_b16 v[146:147], v179 offset:45056
	ds_read_b64_tr_b16 v[148:149], v178 offset:47104
	ds_read_b64_tr_b16 v[160:161], v178 offset:47616
	ds_read_b64_tr_b16 v[158:159], v179 offset:45568
	v_exp_f32_e32 v165, v166
	v_exp_f32_e32 v164, v167
	v_exp_f32_e32 v167, v168
	s_waitcnt lgkmcnt(4)
	v_mfma_f32_32x32x16_bf16 v[82:97], v[2:5], v[154:157], v[82:97]
	v_exp_f32_e32 v166, v169
	v_cvt_pk_bf16_f32 v6, v15, v14
	v_cvt_pk_bf16_f32 v7, v163, v162
	v_cvt_pk_bf16_f32 v8, v165, v164
	v_cvt_pk_bf16_f32 v9, v167, v166
	s_waitcnt lgkmcnt(2)
	v_mfma_f32_32x32x16_bf16 v[34:49], v[10:13], v[146:149], v[34:49]
	ds_read_b64_tr_b16 v[2:3], v179 offset:46080
	ds_read_b64_tr_b16 v[4:5], v178 offset:48128
	ds_read_b64_tr_b16 v[152:153], v178 offset:48640
	ds_read_b64_tr_b16 v[150:151], v179 offset:46592
	v_exp_f32_e32 v147, v170
	v_exp_f32_e32 v146, v171
	v_exp_f32_e32 v149, v172
	s_waitcnt lgkmcnt(4)
	v_mfma_f32_32x32x16_bf16 v[50:65], v[10:13], v[158:161], v[50:65]
	v_exp_f32_e32 v148, v173
	s_waitcnt lgkmcnt(2)
	v_mfma_f32_32x32x16_bf16 v[66:81], v[10:13], v[2:5], v[66:81]
	v_exp_f32_e32 v155, v174
	v_exp_f32_e32 v154, v175
	v_exp_f32_e32 v157, v176
	s_waitcnt lgkmcnt(0)
	v_mfma_f32_32x32x16_bf16 v[82:97], v[10:13], v[150:153], v[82:97]
	v_add_f32_e64 v10, v162, v14
	v_add_f32_e64 v11, v163, v15
	v_exp_f32_e32 v156, v177
	v_add_f32_e32 v10, v164, v10
	v_add_f32_e32 v11, v165, v11
	v_cvt_pk_bf16_f32 v2, v147, v146
	v_cvt_pk_bf16_f32 v3, v149, v148
	v_cvt_pk_bf16_f32 v4, v155, v154
	v_cvt_pk_bf16_f32 v5, v157, v156
	v_add_f32_e32 v10, v166, v10
	v_add_f32_e32 v11, v167, v11
	v_add_f32_e32 v10, v146, v10
	v_add_f32_e32 v11, v147, v11
	v_add_f32_e32 v10, v148, v10
	v_add_f32_e32 v11, v149, v11
	v_add_f32_e32 v10, v154, v10
	v_add_f32_e32 v11, v155, v11
	v_add_f32_e32 v10, v156, v10
	v_add_f32_e32 v11, v157, v11
	v_add_f32_e32 v10, v10, v11
	v_cmp_nge_f32_e32 vcc, s58, v10
	s_cbranch_vccz .LBB0_286
	s_branch .Lslow_4
; __device__ __forceinline__ void apply_mask(bool MASK, f32x16& s0, int kvr, int r, int h) {
;     if (MASK) {
;         asm volatile("" ::: "memory");
;         const int d = r - 4 * h - kvr;
; #pragma unroll
;         for (int i = 0; i < 16; ++i) { if (((i & 3) + 8 * (i >> 2)) > d) s0[i] = -INFINITY; }
;     }
; }
.Lns_308:
	v_cmp_gt_i32_e64 s[34:35], 25, v214
	v_cmp_gt_i32_e64 s[36:37], 26, v214
	v_cmp_gt_i32_e64 s[28:29], 24, v214
	s_and_b64 s[34:35], s[36:37], s[34:35]
	v_cmp_gt_i32_e64 s[26:27], 19, v214
	s_and_b64 s[28:29], s[34:35], s[28:29]
	v_cmp_gt_i32_e64 s[24:25], 18, v214
	s_and_b64 s[26:27], s[28:29], s[26:27]
	v_cmp_gt_i32_e64 s[22:23], 17, v214
	s_and_b64 s[24:25], s[26:27], s[24:25]
	v_cmp_gt_i32_e64 s[20:21], 16, v214
	s_and_b64 s[22:23], s[24:25], s[22:23]
	v_cmp_gt_i32_e64 s[18:19], 11, v214
	s_and_b64 s[20:21], s[22:23], s[20:21]
	v_cmp_gt_i32_e64 s[16:17], 10, v214
	s_and_b64 s[18:19], s[20:21], s[18:19]
	v_cmp_gt_i32_e64 s[14:15], 9, v214
	s_and_b64 s[16:17], s[18:19], s[16:17]
	v_cmp_gt_i32_e64 s[12:13], 8, v214
	s_and_b64 s[14:15], s[16:17], s[14:15]
	v_cmp_gt_i32_e64 s[10:11], 3, v214
	s_and_b64 s[12:13], s[14:15], s[12:13]
	v_cmp_gt_i32_e64 s[8:9], 2, v214
	s_and_b64 s[10:11], s[12:13], s[10:11]
	v_cmp_gt_i32_e64 s[6:7], 1, v214
	s_and_b64 s[8:9], s[10:11], s[8:9]
	v_cmp_gt_i32_e32 vcc, 0, v214
	s_and_b64 s[6:7], s[8:9], s[6:7]
	s_and_b64 vcc, s[6:7], vcc
	v_cndmask_b32_e64 v172, v172, v17, s[36:37]
	v_cndmask_b32_e64 v171, v171, v17, s[34:35]
	v_cndmask_b32_e64 v170, v170, v17, s[28:29]
	v_cndmask_b32_e64 v169, v169, v17, s[26:27]
	v_cndmask_b32_e64 v168, v168, v17, s[24:25]
	v_cndmask_b32_e64 v167, v167, v17, s[22:23]
	v_cndmask_b32_e64 v166, v166, v17, s[20:21]
	v_cndmask_b32_e64 v165, v165, v17, s[18:19]
	v_cndmask_b32_e64 v164, v164, v17, s[16:17]
	v_cndmask_b32_e64 v163, v163, v17, s[14:15]
	v_cndmask_b32_e64 v162, v162, v17, s[12:13]
	v_cndmask_b32_e64 v161, v161, v17, s[10:11]
	v_cndmask_b32_e64 v160, v160, v17, s[8:9]
	v_cndmask_b32_e64 v159, v159, v17, s[6:7]
	v_cndmask_b32_e32 v158, v158, v17, vcc
	v_cmp_gt_i32_e32 vcc, 27, v214
	s_and_saveexec_b64 s[6:7], vcc
	v_mov_b32_e32 v173, s31
	s_or_b64 exec, exec, s[6:7]
	s_branch .Lns_311
.Lns_323:
	v_subrev_u32_e32 v10, 32, v214
	v_cmp_gt_i32_e64 s[34:35], 25, v10
	v_cmp_gt_i32_e64 s[36:37], 26, v10
	v_cmp_gt_i32_e64 s[28:29], 24, v10
	s_and_b64 s[34:35], s[36:37], s[34:35]
	v_cmp_gt_i32_e64 s[26:27], 19, v10
	s_and_b64 s[28:29], s[34:35], s[28:29]
	v_cmp_gt_i32_e64 s[24:25], 18, v10
	s_and_b64 s[26:27], s[28:29], s[26:27]
	v_cmp_gt_i32_e64 s[22:23], 17, v10
	s_and_b64 s[24:25], s[26:27], s[24:25]
	v_cmp_gt_i32_e64 s[20:21], 16, v10
	s_and_b64 s[22:23], s[24:25], s[22:23]
	v_cmp_gt_i32_e64 s[18:19], 11, v10
	s_and_b64 s[20:21], s[22:23], s[20:21]
	v_cmp_gt_i32_e64 s[16:17], 10, v10
	s_and_b64 s[18:19], s[20:21], s[18:19]
	v_cmp_gt_i32_e64 s[14:15], 9, v10
	s_and_b64 s[16:17], s[18:19], s[16:17]
	v_cmp_gt_i32_e64 s[12:13], 8, v10
	s_and_b64 s[14:15], s[16:17], s[14:15]
	v_cmp_gt_i32_e64 s[10:11], 3, v10
	s_and_b64 s[12:13], s[14:15], s[12:13]
	v_cmp_gt_i32_e64 s[8:9], 2, v10
	s_and_b64 s[10:11], s[12:13], s[10:11]
	v_cmp_gt_i32_e64 s[6:7], 1, v10
	s_and_b64 s[8:9], s[10:11], s[8:9]
	v_cmp_gt_i32_e32 vcc, 0, v10
	s_and_b64 s[6:7], s[8:9], s[6:7]
	s_and_b64 vcc, s[6:7], vcc
	v_cndmask_b32_e64 v160, v160, v17, s[36:37]
	v_cndmask_b32_e64 v159, v159, v17, s[34:35]
	v_cndmask_b32_e64 v158, v158, v17, s[28:29]
	v_cndmask_b32_e64 v157, v157, v17, s[26:27]
	v_cndmask_b32_e64 v156, v156, v17, s[24:25]
	v_cndmask_b32_e64 v155, v155, v17, s[22:23]
	v_cndmask_b32_e64 v154, v154, v17, s[20:21]
	v_cndmask_b32_e64 v153, v153, v17, s[18:19]
	v_cndmask_b32_e64 v152, v152, v17, s[16:17]
	v_cndmask_b32_e64 v151, v151, v17, s[14:15]
	v_cndmask_b32_e64 v150, v150, v17, s[12:13]
	v_cndmask_b32_e64 v149, v149, v17, s[10:11]
	v_cndmask_b32_e64 v148, v148, v17, s[8:9]
	v_cndmask_b32_e64 v147, v147, v17, s[6:7]
	v_cndmask_b32_e32 v146, v146, v17, vcc
	v_cmp_gt_i32_e32 vcc, 27, v10
	s_and_saveexec_b64 s[6:7], vcc
	v_mov_b32_e32 v161, s31
	s_or_b64 exec, exec, s[6:7]
	s_branch .Lns_326
.Lns_338:
	v_subrev_u32_e32 v6, 32, v214
	v_cmp_gt_i32_e64 s[34:35], 25, v6
	v_cmp_gt_i32_e64 s[36:37], 26, v6
	v_cmp_gt_i32_e64 s[28:29], 24, v6
	s_and_b64 s[34:35], s[36:37], s[34:35]
	v_cmp_gt_i32_e64 s[26:27], 19, v6
	s_and_b64 s[28:29], s[34:35], s[28:29]
	v_cmp_gt_i32_e64 s[24:25], 18, v6
	s_and_b64 s[26:27], s[28:29], s[26:27]
	v_cmp_gt_i32_e64 s[22:23], 17, v6
	s_and_b64 s[24:25], s[26:27], s[24:25]
	v_cmp_gt_i32_e64 s[20:21], 16, v6
	s_and_b64 s[22:23], s[24:25], s[22:23]
	v_cmp_gt_i32_e64 s[18:19], 11, v6
	s_and_b64 s[20:21], s[22:23], s[20:21]
	v_cmp_gt_i32_e64 s[16:17], 10, v6
	s_and_b64 s[18:19], s[20:21], s[18:19]
	v_cmp_gt_i32_e64 s[14:15], 9, v6
	s_and_b64 s[16:17], s[18:19], s[16:17]
	v_cmp_gt_i32_e64 s[12:13], 8, v6
	s_and_b64 s[14:15], s[16:17], s[14:15]
	v_cmp_gt_i32_e64 s[10:11], 3, v6
	s_and_b64 s[12:13], s[14:15], s[12:13]
	v_cmp_gt_i32_e64 s[8:9], 2, v6
	s_and_b64 s[10:11], s[12:13], s[10:11]
	v_cmp_gt_i32_e64 s[6:7], 1, v6
	s_and_b64 s[8:9], s[10:11], s[8:9]
	v_cmp_gt_i32_e32 vcc, 0, v6
	s_and_b64 s[6:7], s[8:9], s[6:7]
	s_and_b64 vcc, s[6:7], vcc
	v_cndmask_b32_e64 v176, v176, v17, s[36:37]
	v_cndmask_b32_e64 v175, v175, v17, s[34:35]
	v_cndmask_b32_e64 v174, v174, v17, s[28:29]
	v_cndmask_b32_e64 v173, v173, v17, s[26:27]
	v_cndmask_b32_e64 v172, v172, v17, s[24:25]
	v_cndmask_b32_e64 v171, v171, v17, s[22:23]
	v_cndmask_b32_e64 v170, v170, v17, s[20:21]
	v_cndmask_b32_e64 v169, v169, v17, s[18:19]
	v_cndmask_b32_e64 v168, v168, v17, s[16:17]
	v_cndmask_b32_e64 v167, v167, v17, s[14:15]
	v_cndmask_b32_e64 v166, v166, v17, s[12:13]
	v_cndmask_b32_e64 v165, v165, v17, s[10:11]
	v_cndmask_b32_e64 v164, v164, v17, s[8:9]
	v_cndmask_b32_e64 v163, v163, v17, s[6:7]
	v_cndmask_b32_e32 v162, v162, v17, vcc
	v_cmp_gt_i32_e32 vcc, 27, v6
	s_and_saveexec_b64 s[6:7], vcc
	v_mov_b32_e32 v177, s31
	s_or_b64 exec, exec, s[6:7]
	s_branch .Lns_341
